# P0 silu(c): 8 loads in flight instead of one round trip per element; attention: sink and gain loads issued with the q loads before the barrier
# speedup vs baseline: 1.0135x; 1.0053x over previous
.LBB0_17:
	s_lshr_b32 s3, s91, 6
	s_load_dwordx16 s[64:79], s[0:1], 0x0
	s_load_dwordx16 s[12:27], s[0:1], 0x40
	s_cmp_lt_i32 s80, 1
	s_cselect_b64 s[0:1], -1, 0
	s_cmp_gt_i32 s81, 0
	s_cselect_b64 s[4:5], -1, 0
	s_and_b64 s[0:1], s[0:1], s[4:5]
	v_and_b32_e32 v193, 63, v144
	s_andn2_b64 vcc, exec, s[0:1]
	v_lshlrev_b32_e32 v146, 2, v144
	s_cbranch_vccnz .LBB0_103
	v_add_u32_e32 v0, 0, v146
	v_writelane_b32 v244, s46, 0
	v_mov_b32_e32 v147, 0
	v_add_u32_e32 v2, 0xfffffe00, v144
	v_writelane_b32 v244, s47, 1
	s_mov_b64 s[46:47], s[44:45]
	s_mov_b32 s44, s90
	v_add_u32_e32 v3, 0x11000, v0
	s_waitcnt lgkmcnt(0)
	s_add_u32 s4, s66, 0x1000
	s_addc_u32 s5, s67, 0
	s_add_u32 s6, s66, 0x2000
	s_addc_u32 s7, s67, 0
	s_add_u32 s8, s66, 0x3000
	s_addc_u32 s9, s67, 0
	global_load_dword v4, v146, s[66:67]
	global_load_dword v5, v146, s[66:67] offset:2048
	global_load_dword v6, v146, s[4:5]
	global_load_dword v7, v146, s[4:5] offset:2048
	global_load_dword v8, v146, s[6:7]
	global_load_dword v9, v146, s[6:7] offset:2048
	global_load_dword v10, v146, s[8:9]
	global_load_dword v11, v146, s[8:9] offset:2048
	s_waitcnt vmcnt(7)
	v_mul_f32_e32 v12, 0xbfb8aa3b, v4
	v_exp_f32_e32 v12, v12
	s_nop 0
	v_add_f32_e32 v12, 1.0, v12
	v_div_scale_f32 v13, s[10:11], v12, v12, v4
	v_rcp_f32_e32 v14, v13
	v_div_scale_f32 v15, vcc, v4, v12, v4
	v_fma_f32 v16, -v13, v14, 1.0
	v_fmac_f32_e32 v14, v16, v14
	v_mul_f32_e32 v16, v15, v14
	v_fma_f32 v17, -v13, v16, v15
	v_fmac_f32_e32 v16, v17, v14
	v_fma_f32 v13, -v13, v16, v15
	v_div_fmas_f32 v13, v13, v14, v16
	v_div_fixup_f32 v4, v13, v12, v4
	ds_write_b32 v3, v4
	s_waitcnt vmcnt(6)
	v_mul_f32_e32 v12, 0xbfb8aa3b, v5
	v_exp_f32_e32 v12, v12
	s_nop 0
	v_add_f32_e32 v12, 1.0, v12
	v_div_scale_f32 v13, s[10:11], v12, v12, v5
	v_rcp_f32_e32 v14, v13
	v_div_scale_f32 v15, vcc, v5, v12, v5
	v_fma_f32 v16, -v13, v14, 1.0
	v_fmac_f32_e32 v14, v16, v14
	v_mul_f32_e32 v16, v15, v14
	v_fma_f32 v17, -v13, v16, v15
	v_fmac_f32_e32 v16, v17, v14
	v_fma_f32 v13, -v13, v16, v15
	v_div_fmas_f32 v13, v13, v14, v16
	v_div_fixup_f32 v5, v13, v12, v5
	ds_write_b32 v3, v5 offset:2048
	s_waitcnt vmcnt(5)
	v_mul_f32_e32 v12, 0xbfb8aa3b, v6
	v_exp_f32_e32 v12, v12
	s_nop 0
	v_add_f32_e32 v12, 1.0, v12
	v_div_scale_f32 v13, s[10:11], v12, v12, v6
	v_rcp_f32_e32 v14, v13
	v_div_scale_f32 v15, vcc, v6, v12, v6
	v_fma_f32 v16, -v13, v14, 1.0
	v_fmac_f32_e32 v14, v16, v14
	v_mul_f32_e32 v16, v15, v14
	v_fma_f32 v17, -v13, v16, v15
	v_fmac_f32_e32 v16, v17, v14
	v_fma_f32 v13, -v13, v16, v15
	v_div_fmas_f32 v13, v13, v14, v16
	v_div_fixup_f32 v6, v13, v12, v6
	ds_write_b32 v3, v6 offset:4096
	s_waitcnt vmcnt(4)
	v_mul_f32_e32 v12, 0xbfb8aa3b, v7
	v_exp_f32_e32 v12, v12
	s_nop 0
	v_add_f32_e32 v12, 1.0, v12
	v_div_scale_f32 v13, s[10:11], v12, v12, v7
	v_rcp_f32_e32 v14, v13
	v_div_scale_f32 v15, vcc, v7, v12, v7
	v_fma_f32 v16, -v13, v14, 1.0
	v_fmac_f32_e32 v14, v16, v14
	v_mul_f32_e32 v16, v15, v14
	v_fma_f32 v17, -v13, v16, v15
	v_fmac_f32_e32 v16, v17, v14
	v_fma_f32 v13, -v13, v16, v15
	v_div_fmas_f32 v13, v13, v14, v16
	v_div_fixup_f32 v7, v13, v12, v7
	ds_write_b32 v3, v7 offset:6144
	s_waitcnt vmcnt(3)
	v_mul_f32_e32 v12, 0xbfb8aa3b, v8
	v_exp_f32_e32 v12, v12
	s_nop 0
	v_add_f32_e32 v12, 1.0, v12
	v_div_scale_f32 v13, s[10:11], v12, v12, v8
	v_rcp_f32_e32 v14, v13
	v_div_scale_f32 v15, vcc, v8, v12, v8
	v_fma_f32 v16, -v13, v14, 1.0
	v_fmac_f32_e32 v14, v16, v14
	v_mul_f32_e32 v16, v15, v14
	v_fma_f32 v17, -v13, v16, v15
	v_fmac_f32_e32 v16, v17, v14
	v_fma_f32 v13, -v13, v16, v15
	v_div_fmas_f32 v13, v13, v14, v16
	v_div_fixup_f32 v8, v13, v12, v8
	ds_write_b32 v3, v8 offset:8192
	s_waitcnt vmcnt(2)
	v_mul_f32_e32 v12, 0xbfb8aa3b, v9
	v_exp_f32_e32 v12, v12
	s_nop 0
	v_add_f32_e32 v12, 1.0, v12
	v_div_scale_f32 v13, s[10:11], v12, v12, v9
	v_rcp_f32_e32 v14, v13
	v_div_scale_f32 v15, vcc, v9, v12, v9
	v_fma_f32 v16, -v13, v14, 1.0
	v_fmac_f32_e32 v14, v16, v14
	v_mul_f32_e32 v16, v15, v14
	v_fma_f32 v17, -v13, v16, v15
	v_fmac_f32_e32 v16, v17, v14
	v_fma_f32 v13, -v13, v16, v15
	v_div_fmas_f32 v13, v13, v14, v16
	v_div_fixup_f32 v9, v13, v12, v9
	ds_write_b32 v3, v9 offset:10240
	s_waitcnt vmcnt(1)
	v_mul_f32_e32 v12, 0xbfb8aa3b, v10
	v_exp_f32_e32 v12, v12
	s_nop 0
	v_add_f32_e32 v12, 1.0, v12
	v_div_scale_f32 v13, s[10:11], v12, v12, v10
	v_rcp_f32_e32 v14, v13
	v_div_scale_f32 v15, vcc, v10, v12, v10
	v_fma_f32 v16, -v13, v14, 1.0
	v_fmac_f32_e32 v14, v16, v14
	v_mul_f32_e32 v16, v15, v14
	v_fma_f32 v17, -v13, v16, v15
	v_fmac_f32_e32 v16, v17, v14
	v_fma_f32 v13, -v13, v16, v15
	v_div_fmas_f32 v13, v13, v14, v16
	v_div_fixup_f32 v10, v13, v12, v10
	ds_write_b32 v3, v10 offset:12288
	s_waitcnt vmcnt(0)
	v_mul_f32_e32 v12, 0xbfb8aa3b, v11
	v_exp_f32_e32 v12, v12
	s_nop 0
	v_add_f32_e32 v12, 1.0, v12
	v_div_scale_f32 v13, s[10:11], v12, v12, v11
	v_rcp_f32_e32 v14, v13
	v_div_scale_f32 v15, vcc, v11, v12, v11
	v_fma_f32 v16, -v13, v14, 1.0
	v_fmac_f32_e32 v14, v16, v14
	v_mul_f32_e32 v16, v15, v14
	v_fma_f32 v17, -v13, v16, v15
	v_fmac_f32_e32 v16, v17, v14
	v_fma_f32 v13, -v13, v16, v15
	v_div_fmas_f32 v13, v13, v14, v16
	v_div_fixup_f32 v11, v13, v12, v11
	ds_write_b32 v3, v11 offset:14336
	s_lshl_b32 s0, s2, 3
	s_add_i32 s8, s3, s0
	s_cmpk_gt_i32 s8, 0x5ff
	s_waitcnt lgkmcnt(0)
	s_barrier
	s_cbranch_scc1 .LBB0_27
	s_add_u32 s9, s62, 0x1b00000
	s_addc_u32 s10, s63, 0
	s_lshl_b32 s11, s82, 3
	s_add_u32 s28, s68, 0x60000
	s_addc_u32 s29, s69, 0
	s_mov_b32 s30, 0x12000
	s_mov_b32 s31, 0x18000
	s_mov_b32 s34, 0x1e000
	s_mov_b32 s35, 0x24000
	s_mov_b32 s36, 0x2a000
	s_mov_b32 s37, 0x30000
	s_mov_b32 s38, 0x36000
	s_mov_b32 s39, 0x3c000
	s_mov_b32 s40, 0x42000
	s_mov_b32 s41, 0x48000
	s_mov_b32 s42, 0x4e000
	s_mov_b32 s43, 0x54000
	s_mov_b64 s[6:7], 0xc0000
	s_branch .LBB0_23

.Lattn_stage_k23:
	global_load_dwordx4 v[12:15], v252, s[86:87] offset:3072
	global_load_dwordx4 v[230:233], v253, s[86:87] offset:3072
	s_mov_b32 s69, 0
	s_lshl_b32 s70, s68, 3
	s_add_i32 s76, s70, s3
	v_or_b32_e32 v2, s66, v124
	v_mov_b64_e32 v[0:1], s[50:51]
	s_lshl_b32 s84, s76, 6
	v_mad_u64_u32 v[0:1], s[70:71], v2, s95, v[0:1]
	s_ashr_i32 s85, s84, 31
	v_mad_i32_i24 v1, s67, v187, v1
	s_lshl_b64 s[70:71], s[84:85], 1
	s_ashr_i32 s77, s76, 31
	v_lshl_add_u64 v[0:1], v[0:1], 0, s[70:71]
	v_lshlrev_b32_e32 v126, 1, v141
	s_lshl_b64 s[76:77], s[76:77], 2
	v_lshl_add_u64 v[0:1], v[0:1], 0, v[126:127]
	s_add_u32 s76, s78, s76
	global_load_dwordx4 v[48:51], v[0:1], off nt
	global_load_dwordx4 v[108:111], v[0:1], off offset:32 nt
	global_load_dwordx4 v[104:107], v[0:1], off offset:64 nt
	global_load_dwordx4 v[120:123], v[0:1], off offset:96 nt
	s_addc_u32 s77, s79, s77
	global_load_dword v16, v127, s[76:77]
	v_lshl_add_u64 v[0:1], s[84:85], 2, v[138:139]
	global_load_dwordx4 v[80:83], v[0:1], off
	global_load_dwordx4 v[84:87], v[0:1], off offset:16
	s_waitcnt vmcnt(8)
	ds_write_b128 v186, v[4:7]
	ds_write_b128 v176, v[8:11]
	ds_write_b128 v177, v[12:15]
	ds_write_b16 v179, v234 offset:36864
	ds_write_b16_d16_hi v179, v234 offset:37392
	ds_write_b16 v179, v235 offset:37920
	ds_write_b16_d16_hi v179, v235 offset:38448
	ds_write_b16 v179, v236 offset:38976
	ds_write_b16_d16_hi v179, v236 offset:39504
	ds_write_b16 v179, v237 offset:40032
	ds_write_b16_d16_hi v179, v237 offset:40560
	ds_write_b16 v180, v238 offset:36864
	ds_write_b16_d16_hi v180, v238 offset:37392
	ds_write_b16 v180, v239 offset:37920
	ds_write_b16_d16_hi v180, v239 offset:38448
	ds_write_b16 v180, v240 offset:38976
	ds_write_b16_d16_hi v180, v240 offset:39504
	ds_write_b16 v180, v241 offset:40032
	ds_write_b16_d16_hi v180, v241 offset:40560
	ds_write_b16 v181, v242 offset:36864
	ds_write_b16_d16_hi v181, v242 offset:37392
	ds_write_b16 v181, v243 offset:37920
	ds_write_b16_d16_hi v181, v243 offset:38448
	ds_write_b16 v181, v244 offset:38976
	ds_write_b16_d16_hi v181, v244 offset:39504
	ds_write_b16 v181, v245 offset:40032
	ds_write_b16_d16_hi v181, v245 offset:40560
	ds_write_b16 v182, v246 offset:36864
	ds_write_b16_d16_hi v182, v246 offset:37392
	ds_write_b16 v182, v247 offset:37920
	ds_write_b16_d16_hi v182, v247 offset:38448
	ds_write_b16 v182, v248 offset:38976
	ds_write_b16_d16_hi v182, v248 offset:39504
	ds_write_b16 v182, v249 offset:40032
	ds_write_b16_d16_hi v182, v249 offset:40560
	s_waitcnt vmcnt(7)
	ds_write_b128 v178, v[230:233]
	s_waitcnt lgkmcnt(0)
	s_barrier
	s_mul_i32 s85, s72, 0x9000000
	s_cmp_eq_u32 s99, 0
	s_mul_hi_i32 s84, s72, 0x9000000
	v_lshl_add_u64 v[0:1], v[124:125], 0, s[74:75]
	s_cselect_b64 s[72:73], -1, 0
	s_add_u32 s74, s70, s85
	s_addc_u32 s75, s71, s84
	v_mov_b64_e32 v[2:3], s[74:75]
	v_mad_u64_u32 v[2:3], s[74:75], v0, s95, v[2:3]
	v_mad_i32_i24 v3, v1, s95, v3
	v_mov_b32_e32 v151, v173
	v_mov_b32_e32 v153, v172
	s_mov_b32 s76, 0
	s_mov_b32 s77, 0
	v_lshl_add_u64 v[162:163], v[142:143], 0, s[70:71]
	v_lshl_add_u64 v[164:165], v[148:149], 0, v[2:3]
	s_waitcnt vmcnt(6)
	v_mov_b64_e32 v[90:91], v[50:51]
	s_waitcnt vmcnt(5)
	v_mov_b64_e32 v[92:93], v[108:109]
	s_waitcnt vmcnt(4)
	v_mov_b64_e32 v[96:97], v[104:105]
	s_waitcnt vmcnt(3)
	v_mov_b64_e32 v[100:101], v[120:121]
	v_mov_b64_e32 v[88:89], v[48:49]
	v_mov_b64_e32 v[94:95], v[110:111]
	v_mov_b64_e32 v[98:99], v[106:107]
	v_mov_b64_e32 v[102:103], v[122:123]
	s_waitcnt vmcnt(2)
	v_mul_f32_e32 v155, 0x3fb8aa3b, v16
	s_branch .LBB0_315
